# P4 SSD-output queue: next unit index prefetched during the current unit (measure 1)
# baseline (speedup 1.0000x reference)
; #define LAS __attribute__((address_space(3)))
; #define QUEUE_LOOP(qi, total, ...) for (;;) { __syncthreads(); if (threadIdx.x == 0) ctlw[16] = __hip_atomic_fetch_add(qbase + 64 * (qi), 1u, __ATOMIC_RELAXED, __HIP_MEMORY_SCOPE_AGENT); \
;         __syncthreads(); const int u = (int)ctlw[16]; if (u >= (total)) break; __VA_ARGS__ }
; __device__ __forceinline__ void phase4(const Params& p, LAS unsigned char* lds, volatile LAS unsigned* ctlw, int vcu, int G, int qset) {
;     const int tid = threadIdx.x, lane = tid & 63, wave = __builtin_amdgcn_readfirstlane(tid >> 6);
;     bf16_t* MIX = (bf16_t*)(p.ws + WS_MIX);
;     const bf16_t* PROJ = (const bf16_t*)(p.ws + WS_PROJ);
;     unsigned* qbase = (unsigned*)(p.ws + WS_CTL) + CW_QUEUE + 1024 * qset;
;     ...
;     QUEUE_LOOP(5, NBATCH * 16 * 8, { const int v = NBATCH * 16 * 8 - 1 - u;
.LBB0_1074:
	s_add_u32 s6, s90, 0x14e00000
	s_addc_u32 s7, s91, 0
	s_add_u32 s8, s90, 0xd200000
	s_addc_u32 s9, s91, 0
	s_add_u32 s10, s88, 0x8080000
	s_addc_u32 s11, s89, 0
	s_add_u32 s12, s90, 0x13c00000
	s_addc_u32 s13, s91, 0
	s_add_u32 s14, s90, 0xdd00000
	s_addc_u32 s15, s91, 0
	s_add_u32 s24, s90, 0xe000000
	s_addc_u32 s28, s91, 0
	s_add_u32 s16, s90, 0x16200004
	s_addc_u32 s17, s91, 0
	s_add_i32 s29, 0, 0x27e40
	s_waitcnt vmcnt(0)
	v_mbcnt_hi_u32_b32 v75, -1, v190
	v_bfrev_b32_e32 v2, 0.5
	s_mov_b32 s5, 0
	v_cmp_eq_u32_e64 s[0:1], 0, v0
	v_mov_b32_e32 v51, 0
	v_mov_b32_e32 v1, s29
	s_movk_i32 s30, 0x1ff
	s_add_i32 s31, 0, 0x1e000
	s_movk_i32 s33, 0x100
	s_add_i32 s34, 0, 0x1e200
	s_add_i32 s35, 0, 0x1e1fc
	s_movk_i32 s40, 0x2000
	s_movk_i32 s41, 0x4000
	s_add_i32 s42, 0, 0x1e404
	s_add_i32 s43, 0, 0x1e408
	s_movk_i32 s44, 0x80
	s_add_i32 s45, 0, 0x1e40c
	s_add_i32 s46, 0, 0x1e410
	s_add_i32 s47, 0, 0x1e414
	s_add_i32 s48, 0, 0x1e418
	s_add_i32 s49, 0, 0x1e41c
	s_add_i32 s50, 0, 0x1e420
	s_add_i32 s51, 0, 0x1e424
	s_add_i32 s52, 0, 0x1e428
	s_add_i32 s53, 0, 0x1e42c
	s_add_i32 s54, 0, 0x1e430
	s_add_i32 s55, 0, 0x1e434
	s_add_i32 s62, 0, 0x1e438
	s_add_i32 s63, 0, 0x1e43c
	s_add_i32 s64, 0, 0x15400
	s_movk_i32 s65, 0x110
	s_add_i32 s66, 0, 0x19800
	s_movk_i32 s67, 0x90
	s_add_i32 s68, 0, 0x11000
	s_movk_i32 s69, 0x3600
	s_mov_b64 s[18:19], 0x5a02000
	v_and_b32_e32 v77, 64, v75
	v_add_u32_e32 v79, -1, v75
	v_add_u32_e32 v80, -2, v75
	v_add_u32_e32 v81, -4, v75
	v_add_u32_e32 v82, -8, v75
	v_add_u32_e32 v83, -16, v75
	v_subrev_u32_e32 v84, 32, v75
	v_lshl_or_b32 v85, v75, 2, v2
	s_and_saveexec_b64 s[2:3], s[0:1]
	s_cbranch_execz .Lp4q_init
	v_mov_b32_e32 v255, 1
	global_atomic_add v255, v51, v255, s[90:91] offset:1536 sc0
.Lp4q_init:
	s_or_b64 exec, exec, s[2:3]
	s_branch .LBB0_1077

; #define QUEUE_LOOP(qi, total, ...) for (;;) { __syncthreads(); if (threadIdx.x == 0) ctlw[16] = __hip_atomic_fetch_add(qbase + 64 * (qi), 1u, __ATOMIC_RELAXED, __HIP_MEMORY_SCOPE_AGENT); \
;         __syncthreads(); const int u = (int)ctlw[16]; if (u >= (total)) break; __VA_ARGS__ }
; __device__ __forceinline__ void phase4(const Params& p, LAS unsigned char* lds, volatile LAS unsigned* ctlw, int vcu, int G, int qset) {
;     ...
;     QUEUE_LOOP(5, NBATCH * 16 * 8, { const int v = NBATCH * 16 * 8 - 1 - u;
;         ssd_out_unit<false>(p.ws, p.out, p.in[I_ALOG], p.in[I_DSKIP], p.in[I_SSDNW], p.in[I_SSM], p.in[I_SCONV], p.in[I_CONVW], p.in[I_CONVB], lds, (v >> 3) & 3, v >> 5, v & 7); })
.LBB0_1080:
	s_or_b64 exec, exec, s[20:21]
	s_waitcnt vmcnt(0) lgkmcnt(0)
	v_mov_b32_e32 v3, v255
	s_nop 0
	v_readfirstlane_b32 s4, v3
	v_mov_b32_e32 v3, s29
	s_nop 0
	v_add_u32_e32 v2, s4, v2
	ds_write_b32 v3, v2
.LBB0_1081:
	s_or_b64 exec, exec, s[2:3]
	s_waitcnt lgkmcnt(0)
	s_barrier
	ds_read_b32 v2, v1
	s_mov_b64 s[2:3], -1
	s_waitcnt lgkmcnt(0)
	v_cmp_lt_i32_e32 vcc, s30, v2
	v_readfirstlane_b32 s73, v2
	s_cbranch_vccnz .LBB0_1076
	s_and_saveexec_b64 s[22:23], s[0:1]
	s_cbranch_execz .Lp4q_next
	v_mov_b32_e32 v255, 1
	global_atomic_add v255, v51, v255, s[90:91] offset:1536 sc0
.Lp4q_next:
	s_or_b64 exec, exec, s[22:23]
	s_sub_i32 s74, 0x1ff, s73
	s_and_b32 s70, s74, 7
	s_lshl_b32 s20, s70, 2
	v_mov_b32_e32 v88, v0
	v_mov_b32_e32 v2, s20
	global_load_dword v4, v2, s[56:57]
	global_load_dword v53, v2, s[58:59]
	v_readfirstlane_b32 s21, v88
	s_lshr_b32 s72, s74, 5
	s_ashr_i32 s4, s21, 6
	v_and_b32_e32 v86, 63, v88
	s_and_b32 s71, s74, 31
	s_cmp_gt_u32 s21, 63
	v_cmp_gt_u32_e32 vcc, 16, v86
	s_barrier
	s_cbranch_scc0 .LBB0_1090
	s_cmp_eq_u32 s4, 1
	s_cselect_b64 s[2:3], -1, 0
	s_and_b64 s[22:23], s[2:3], vcc
	s_and_saveexec_b64 s[2:3], s[22:23]
	s_cbranch_execz .LBB0_1089
	v_add_u32_e32 v5, 1, v86
	v_cmp_gt_u32_e32 vcc, s72, v5
	s_lshl_b32 s21, s71, 4
	v_add_lshl_u32 v50, s21, v86, 2
	v_mov_b32_e32 v6, 0
	s_and_saveexec_b64 s[22:23], vcc
	s_cbranch_execz .Lfac_noload
	global_load_dword v6, v50, s[16:17]
